# attention static priority raise moved to the older half (waves 0-3) instead of waves 4-7, per-half A/B
# speedup vs baseline: 1.0027x; 1.0027x over previous
; #define GSYNC() do { if constexpr (SEL < 0) { XcdBarrier b_; b_.bar = (unsigned*)(karg_ws() + WS_BAR); b_.x = xb_xcc_id(); b_.st = (volatile LAS unsigned*)(ldsp + attn_body::LDS_BYTES); xcd_barrier(b_, wv); } } while (0)
; #define PHASE(id) if constexpr (SEL < 0 || SEL == (id))
; #define q_ctl ((unsigned*)(karg_ws() + WS_CTL))
; #define q_cum ((float*)(karg_ws() + WS_CUM))
; template <int l, int SEL> __device__ __forceinline__ void layer_body(const Args& args, LAS unsigned char* ldsp, unsigned char* lds, const int G, const int bx, const int vcu, const int wv) {
;     ...
;         GSYNC();
;         PHASE(B + 1) {
;             typedef attn_body::bf16 abf;
;             const abf* pj = (const abf*)q_proj;
;     ...
;             for (int p = vcu; p < 256; p += G) { const int vh = p >> 5, s = p & 31;
;                 const unsigned* nr = q_ctl + 16; const float qn = sqrtf(__uint_as_float(nr[2 * vh]) + __uint_as_float(nr[2 * vh + 1])), kn = sqrtf(__uint_as_float(nr[16 + 2 * vh]) + __uint_as_float(nr[16 + 2 * vh + 1]));
;                 const float thr = 2.04f * qn * kn + 40.f;
;                 for (int half = 0; half < 2; ++half) { const int qb = half ? 63 - s : s;
;                     attn_body::attn_unit<0, 8>(qb, pj + (size_t)vh * M * 64, pj + (size_t)(8 + vh) * M * 64, pj + (size_t)(16 + vh) * M * 64, (abf*)q_yatt + vh * 64, q_cum + (size_t)vh * M, nullptr, thr, (char*)lds, wv); } }
.LBB0_362:
	s_or_b64 exec, exec, s[4:5]
	s_cmpk_lt_i32 s76, 0x100
	s_cselect_b64 s[6:7], -1, 0
	v_writelane_b32 v255, s6, 2
	s_mov_b64 s[4:5], s[0:1]
	s_cmpk_gt_i32 s76, 0xff
	v_writelane_b32 v255, s7, 3
	s_waitcnt lgkmcnt(0)
	s_barrier
	s_cbranch_scc1 .LBB0_544
	s_cmp_gt_u32 s68, 3
	s_cbranch_scc1 .Lprio_l0
	s_setprio 1

; #define GSYNC() do { if constexpr (SEL < 0) { XcdBarrier b_; b_.bar = (unsigned*)(karg_ws() + WS_BAR); b_.x = xb_xcc_id(); b_.st = (volatile LAS unsigned*)(ldsp + attn_body::LDS_BYTES); xcd_barrier(b_, wv); } } while (0)
; #define PHASE(id) if constexpr (SEL < 0 || SEL == (id))
; #define q_ctl ((unsigned*)(karg_ws() + WS_CTL))
; #define q_cum ((float*)(karg_ws() + WS_CUM))
; template <int l, int SEL> __device__ __forceinline__ void layer_body(const Args& args, LAS unsigned char* ldsp, unsigned char* lds, const int G, const int bx, const int vcu, const int wv) {
;     ...
;         GSYNC();
;         PHASE(B + 1) {
;             typedef attn_body::bf16 abf;
;             const abf* pj = (const abf*)q_proj;
;     ...
;             for (int p = vcu; p < 256; p += G) { const int vh = p >> 5, s = p & 31;
;                 const unsigned* nr = q_ctl + 16; const float qn = sqrtf(__uint_as_float(nr[2 * vh]) + __uint_as_float(nr[2 * vh + 1])), kn = sqrtf(__uint_as_float(nr[16 + 2 * vh]) + __uint_as_float(nr[16 + 2 * vh + 1]));
;                 const float thr = 2.04f * qn * kn + 40.f;
;                 for (int half = 0; half < 2; ++half) { const int qb = half ? 63 - s : s;
;                     attn_body::attn_unit<0, 8>(qb, pj + (size_t)vh * M * 64, pj + (size_t)(8 + vh) * M * 64, pj + (size_t)(16 + vh) * M * 64, (abf*)q_yatt + vh * 64, q_cum + (size_t)vh * M, nullptr, thr, (char*)lds, wv); } }
.LBB0_1402:
	s_or_b64 exec, exec, s[8:9]
	v_readlane_b32 s10, v255, 2
	v_readlane_b32 s11, v255, 3
	s_mov_b64 s[8:9], s[0:1]
	s_andn2_b64 vcc, exec, s[10:11]
	s_waitcnt lgkmcnt(0)
	s_barrier
	s_cbranch_vccnz .LBB0_1584
	s_cmp_gt_u32 s68, 3
	s_cbranch_scc1 .Lprio_l1
	s_setprio 1
